# v50: prep K-cache and V-cache conversion loops hand-unrolled x2 (both items' loads in flight together)
# speedup vs baseline: 1.0065x; 1.0003x over previous
; __device__ __forceinline__ unsigned pk2(float lo, float hi) { f32x2 v = {lo, hi}; bf16v2_t b = __builtin_convertvector(v, bf16v2_t); return __builtin_bit_cast(unsigned, b); }
; __device__ __forceinline__ void prep_phase(const Params& p, char* lds) {
;     ...
;     for (int i = gt; i < 128 * 128 * 16; i += NGT) {
;       const int c8 = i & 15, w = (i >> 4) & 127, b = i >> 11;
;       const float* s = ck + ((size_t)b * 128 + w) * 128 + c8 * 8;
;       const f32x4 a = *(const f32x4*)s, bq = *(const f32x4*)(s + 4);
;       u32x4 o; o.x = pk2(a.x, a.y); o.y = pk2(a.z, a.w); o.z = pk2(bq.x, bq.y); o.w = pk2(bq.z, bq.w);
;       *(u32x4*)(Ks + ((size_t)b * 144 + w) * 128 + c8 * 8) = o;
;     }
.LBB0_40:
	s_or_b64 exec, exec, s[0:1]
	v_readlane_b32 s4, v244, 0
	v_readlane_b32 s6, v244, 2
	s_mov_b32 s0, 0x40000
	v_readlane_b32 s5, v244, 1
	v_readlane_b32 s7, v244, 3
	s_add_u32 s24, s6, 0xad00000
	v_cmp_gt_i32_e64 s[0:1], s0, v186
	s_addc_u32 s25, s7, 0
	s_and_saveexec_b64 s[4:5], s[0:1]
	v_readlane_b32 s8, v244, 14
	v_readlane_b32 s14, v244, 20
	v_readlane_b32 s15, v244, 21
	v_readlane_b32 s12, v244, 18
	v_readlane_b32 s13, v244, 19
	s_mov_b64 s[14:15], s[24:25]
	v_readlane_b32 s9, v244, 15
	v_readlane_b32 s10, v244, 16
	v_readlane_b32 s11, v244, 17
	v_readlane_b32 s16, v244, 22
	v_readlane_b32 s17, v244, 23
	v_readlane_b32 s18, v244, 24
	v_readlane_b32 s19, v244, 25
	v_readlane_b32 s20, v244, 26
	v_readlane_b32 s21, v244, 27
	v_readlane_b32 s22, v244, 28
	v_readlane_b32 s23, v244, 29
	s_cbranch_execz .LBB0_43
	v_readlane_b32 s3, v244, 33
	s_mov_b64 s[6:7], 0
	v_mov_b32_e32 v3, 0
	v_lshl_or_b32 v1, s3, 12, v43
	s_lshl_b32 s3, s33, 12
	s_mov_b32 s8, 0x3ffff
	v_mov_b32_e32 v4, v186
	s_cmp_lg_u32 s33, 0x100
	s_cbranch_scc1 .LBB0_42
	v_ashrrev_i32_e32 v14, 11, v4
	v_ashrrev_i32_e32 v15, 31, v14
	v_bfe_u32 v2, v4, 4, 7
	v_lshlrev_b64 v[10:11], 16, v[14:15]
	v_mov_b32_e32 v7, v3
	v_and_b32_e32 v5, 0x78, v1
	v_lshlrev_b32_e32 v6, 9, v2
	v_lshl_add_u64 v[10:11], s[12:13], 0, v[10:11]
	v_mov_b32_e32 v9, v3
	v_lshlrev_b32_e32 v8, 2, v5
	v_lshl_add_u64 v[6:7], v[10:11], 0, v[6:7]
	v_lshl_add_u64 v[10:11], v[6:7], 0, v[8:9]
	global_load_dwordx4 v[6:9], v[10:11], off
	s_nop 0
	global_load_dwordx4 v[10:13], v[10:11], off offset:16
	v_mul_hi_i32_i24_e32 v15, 0x90, v14
	v_mul_i32_i24_e32 v14, 0x90, v14
	v_lshl_add_u64 v[14:15], v[14:15], 0, v[2:3]
	v_lshlrev_b64 v[14:15], 8, v[14:15]
	v_lshlrev_b32_e32 v2, 1, v5
	v_lshl_add_u64 v[14:15], s[14:15], 0, v[14:15]
	v_lshl_add_u64 v[14:15], v[14:15], 0, v[2:3]
	v_add_u32_e32 v54, s2, v4
	v_add_u32_e32 v51, s3, v1
	v_mov_b32_e32 v53, 0
	v_ashrrev_i32_e32 v64, 11, v54
	v_ashrrev_i32_e32 v65, 31, v64
	v_bfe_u32 v52, v54, 4, 7
	v_lshlrev_b64 v[60:61], 16, v[64:65]
	v_mov_b32_e32 v57, v53
	v_and_b32_e32 v55, 0x78, v51
	v_lshlrev_b32_e32 v56, 9, v52
	v_lshl_add_u64 v[60:61], s[12:13], 0, v[60:61]
	v_mov_b32_e32 v59, v53
	v_lshlrev_b32_e32 v58, 2, v55
	v_lshl_add_u64 v[56:57], v[60:61], 0, v[56:57]
	v_lshl_add_u64 v[60:61], v[56:57], 0, v[58:59]
	global_load_dwordx4 v[56:59], v[60:61], off
	s_nop 0
	global_load_dwordx4 v[60:63], v[60:61], off offset:16
	v_mul_hi_i32_i24_e32 v65, 0x90, v64
	v_mul_i32_i24_e32 v64, 0x90, v64
	v_lshl_add_u64 v[64:65], v[64:65], 0, v[52:53]
	v_lshlrev_b64 v[64:65], 8, v[64:65]
	v_lshlrev_b32_e32 v52, 1, v55
	v_lshl_add_u64 v[64:65], s[14:15], 0, v[64:65]
	v_lshl_add_u64 v[64:65], v[64:65], 0, v[52:53]
	s_waitcnt vmcnt(3)
	v_cvt_pk_bf16_f32 v6, v6, v7
	v_cvt_pk_bf16_f32 v7, v8, v9
	s_waitcnt vmcnt(2)
	v_cvt_pk_bf16_f32 v8, v10, v11
	v_cvt_pk_bf16_f32 v9, v12, v13
	global_store_dwordx4 v[14:15], v[6:9], off
	s_waitcnt vmcnt(2)
	v_cvt_pk_bf16_f32 v56, v56, v57
	v_cvt_pk_bf16_f32 v57, v58, v59
	s_waitcnt vmcnt(1)
	v_cvt_pk_bf16_f32 v58, v60, v61
	v_cvt_pk_bf16_f32 v59, v62, v63
	global_store_dwordx4 v[64:65], v[56:59], off
	s_branch .LBB0_43

; __device__ __forceinline__ unsigned pk2(float lo, float hi) { f32x2 v = {lo, hi}; bf16v2_t b = __builtin_convertvector(v, bf16v2_t); return __builtin_bit_cast(unsigned, b); }
; __device__ __forceinline__ void prep_phase(const Params& p, char* lds) {
;     ...
;     for (int i = gt; i < 128 * 16 * 128; i += NGT) {
;       const int kvd = i & 127, w8 = (i >> 7) & 15, b = i >> 11;
;       const float* s = cv + ((size_t)b * 128 + w8 * 8) * 128 + kvd;
;       u32x4 o; o.x = pk2(s[0], s[128]); o.y = pk2(s[256], s[384]); o.z = pk2(s[512], s[640]); o.w = pk2(s[768], s[896]);
;       *(u32x4*)(Vts + ((size_t)b * 128 + kvd) * 144 + w8 * 8) = o;
;     }
.LBB0_46:
	s_or_b64 exec, exec, s[4:5]
	v_readlane_b32 s4, v244, 0
	v_readlane_b32 s6, v244, 2
	v_readlane_b32 s5, v244, 1
	v_readlane_b32 s7, v244, 3
	s_add_u32 s4, s6, 0xb180000
	s_addc_u32 s5, s7, 0
	v_writelane_b32 v244, s4, 53
	s_nop 1
	v_writelane_b32 v244, s5, 54
	s_and_saveexec_b64 s[4:5], s[0:1]
	v_writelane_b32 v244, s14, 55
	s_nop 1
	v_writelane_b32 v244, s15, 56
	s_cbranch_execz .LBB0_49
	v_and_b32_e32 v2, 0x7f, v0
	v_readlane_b32 s8, v244, 14
	v_readlane_b32 s6, v244, 53
	v_mov_b32_e32 v5, 0
	v_lshlrev_b32_e32 v4, 2, v2
	v_readlane_b32 s14, v244, 20
	v_readlane_b32 s15, v244, 21
	v_readlane_b32 s7, v244, 54
	s_mov_b64 s[0:1], 0
	v_lshl_add_u64 v[6:7], s[14:15], 0, v[4:5]
	s_movk_i32 s3, 0x120
	v_mov_b64_e32 v[8:9], s[6:7]
	s_mov_b32 s6, 0x3ffff
	v_mov_b32_e32 v1, v186
	v_readlane_b32 s9, v244, 15
	v_readlane_b32 s10, v244, 16
	v_readlane_b32 s11, v244, 17
	v_readlane_b32 s12, v244, 18
	v_readlane_b32 s13, v244, 19
	v_readlane_b32 s16, v244, 22
	v_readlane_b32 s17, v244, 23
	v_readlane_b32 s18, v244, 24
	v_readlane_b32 s19, v244, 25
	v_readlane_b32 s20, v244, 26
	v_readlane_b32 s21, v244, 27
	v_readlane_b32 s22, v244, 28
	v_readlane_b32 s23, v244, 29
	s_cmp_lg_u32 s33, 0x100
	s_cbranch_scc1 .LBB0_48
	v_ashrrev_i32_e32 v10, 11, v1
	v_lshrrev_b32_e32 v3, 4, v1
	v_ashrrev_i32_e32 v11, 31, v10
	v_and_b32_e32 v3, 0x78, v3
	v_lshlrev_b64 v[10:11], 7, v[10:11]
	v_or_b32_e32 v12, v10, v3
	v_mov_b32_e32 v13, v11
	v_lshlrev_b64 v[12:13], 9, v[12:13]
	v_lshl_add_u64 v[12:13], v[6:7], 0, v[12:13]
	global_load_dword v16, v[12:13], off
	global_load_dword v17, v[12:13], off offset:512
	global_load_dword v18, v[12:13], off offset:1024
	global_load_dword v19, v[12:13], off offset:1536
	global_load_dword v20, v[12:13], off offset:2048
	global_load_dword v21, v[12:13], off offset:2560
	global_load_dword v22, v[12:13], off offset:3072
	s_nop 0
	global_load_dword v13, v[12:13], off offset:3584
	v_lshlrev_b32_e32 v4, 1, v3
	v_or_b32_e32 v3, v10, v2
	v_mad_i64_i32 v[10:11], s[8:9], v3, s3, v[8:9]
	v_lshl_add_u64 v[14:15], v[10:11], 0, v[4:5]
	v_add_u32_e32 v60, s2, v1
	v_mov_b32_e32 v65, 0
	v_ashrrev_i32_e32 v70, 11, v60
	v_lshrrev_b32_e32 v63, 4, v60
	v_ashrrev_i32_e32 v71, 31, v70
	v_and_b32_e32 v63, 0x78, v63
	v_lshlrev_b64 v[70:71], 7, v[70:71]
	v_or_b32_e32 v72, v70, v63
	v_mov_b32_e32 v73, v71
	v_lshlrev_b64 v[72:73], 9, v[72:73]
	v_lshl_add_u64 v[72:73], v[6:7], 0, v[72:73]
	global_load_dword v76, v[72:73], off
	global_load_dword v77, v[72:73], off offset:512
	global_load_dword v78, v[72:73], off offset:1024
	global_load_dword v79, v[72:73], off offset:1536
	global_load_dword v80, v[72:73], off offset:2048
	global_load_dword v81, v[72:73], off offset:2560
	global_load_dword v82, v[72:73], off offset:3072
	s_nop 0
	global_load_dword v73, v[72:73], off offset:3584
	v_lshlrev_b32_e32 v64, 1, v63
	v_or_b32_e32 v63, v70, v2
	v_mad_i64_i32 v[70:71], s[8:9], v63, s3, v[8:9]
	v_lshl_add_u64 v[74:75], v[70:71], 0, v[64:65]
	s_waitcnt vmcnt(14)
	v_cvt_pk_bf16_f32 v10, v16, v17
	s_waitcnt vmcnt(12)
	v_cvt_pk_bf16_f32 v11, v18, v19
	s_waitcnt vmcnt(10)
	v_cvt_pk_bf16_f32 v12, v20, v21
	s_waitcnt vmcnt(8)
	v_cvt_pk_bf16_f32 v13, v22, v13
	global_store_dwordx4 v[14:15], v[10:13], off
	s_waitcnt vmcnt(7)
	v_cvt_pk_bf16_f32 v70, v76, v77
	s_waitcnt vmcnt(5)
	v_cvt_pk_bf16_f32 v71, v78, v79
	s_waitcnt vmcnt(3)
	v_cvt_pk_bf16_f32 v72, v80, v81
	s_waitcnt vmcnt(1)
	v_cvt_pk_bf16_f32 v73, v82, v73
	global_store_dwordx4 v[74:75], v[70:73], off
	s_branch .LBB0_49
